# code placement: every 16x16x32 MFMA run in the three GEMM K-loops starts 8-byte aligned (7 s_nop 0 pads in load segments)
# speedup vs baseline: 1.0011x; 1.0006x over previous
.LBB0_124:
	s_add_u32 s34, s8, 0xfffc0080
	s_addc_u32 s35, s9, -1
	s_add_i32 s49, 0, 0x10000
	s_cmp_eq_u32 s48, 12
	s_cselect_b32 s37, s23, s35
	s_cselect_b32 s36, s29, s34
	s_cselect_b32 s35, s21, s47
	s_cselect_b32 s34, s31, s46
	s_add_i32 s52, 0, 0x14000
	v_add_u32_e32 v76, s49, v233
	v_add_u32_e32 v132, s52, v233
	ds_read_b128 v[56:59], v76
	ds_read_b128 v[60:63], v76 offset:1024
	ds_read_b128 v[68:71], v76 offset:2048
	ds_read_b128 v[76:79], v76 offset:3072
	ds_read_b128 v[104:107], v132
	ds_read_b128 v[108:111], v132 offset:1024
	ds_read_b128 v[124:127], v132 offset:2048
	ds_read_b128 v[132:135], v132 offset:3072
	v_lshl_add_u64 v[208:209], s[8:9], 0, v[206:207]
	s_add_i32 m0, s39, 0xc000
	ds_read_b128 v[152:155], v235
	ds_read_b128 v[156:159], v235 offset:1024
	ds_read_b128 v[168:171], v235 offset:2048
	ds_read_b128 v[172:175], v235 offset:3072
	ds_read_b128 v[176:179], v235 offset:4096
	ds_read_b128 v[180:183], v235 offset:5120
	ds_read_b128 v[184:187], v235 offset:6144
	ds_read_b128 v[188:191], v235 offset:7168
	global_load_lds_dwordx4 v[208:209], off
	v_lshl_add_u64 v[208:209], s[8:9], 0, v[204:205]
	s_add_i32 m0, s39, 0xe000
	s_nop 0
	global_load_lds_dwordx4 v[208:209], off
	s_waitcnt vmcnt(8)
	s_waitcnt lgkmcnt(0)
	s_barrier
	s_setprio 1
	s_waitcnt lgkmcnt(0)
	v_mfma_f32_16x16x32_bf16 v[164:167], v[56:59], v[152:155], v[164:167]
	v_mfma_f32_16x16x32_bf16 v[160:163], v[68:71], v[152:155], v[160:163]
	v_mfma_f32_16x16x32_bf16 v[140:143], v[56:59], v[168:171], v[140:143]
	v_mfma_f32_16x16x32_bf16 v[136:139], v[68:71], v[168:171], v[136:139]
	v_mfma_f32_16x16x32_bf16 v[116:119], v[56:59], v[176:179], v[116:119]
	v_mfma_f32_16x16x32_bf16 v[112:115], v[68:71], v[176:179], v[112:115]
	v_mfma_f32_16x16x32_bf16 v[92:95], v[56:59], v[184:187], v[92:95]
	v_mfma_f32_16x16x32_bf16 v[88:91], v[68:71], v[184:187], v[88:91]
	v_mfma_f32_16x16x32_bf16 v[164:167], v[60:63], v[156:159], v[164:167]
	v_mfma_f32_16x16x32_bf16 v[160:163], v[76:79], v[156:159], v[160:163]
	v_mfma_f32_16x16x32_bf16 v[140:143], v[60:63], v[172:175], v[140:143]
	v_mfma_f32_16x16x32_bf16 v[136:139], v[76:79], v[172:175], v[136:139]
	v_mfma_f32_16x16x32_bf16 v[116:119], v[60:63], v[180:183], v[116:119]
	v_mfma_f32_16x16x32_bf16 v[112:115], v[76:79], v[180:183], v[112:115]
	v_mfma_f32_16x16x32_bf16 v[92:95], v[60:63], v[188:191], v[92:95]
	v_mfma_f32_16x16x32_bf16 v[88:91], v[76:79], v[188:191], v[88:91]
	s_setprio 0
	s_setprio 1
	v_mfma_f32_16x16x32_bf16 v[148:151], v[104:107], v[152:155], v[148:151]
	v_mfma_f32_16x16x32_bf16 v[144:147], v[124:127], v[152:155], v[144:147]
	v_mfma_f32_16x16x32_bf16 v[128:131], v[104:107], v[168:171], v[128:131]
	v_mfma_f32_16x16x32_bf16 v[120:123], v[124:127], v[168:171], v[120:123]
	v_mfma_f32_16x16x32_bf16 v[100:103], v[104:107], v[176:179], v[100:103]
	v_mfma_f32_16x16x32_bf16 v[96:99], v[124:127], v[176:179], v[96:99]
	v_mfma_f32_16x16x32_bf16 v[84:87], v[104:107], v[184:187], v[84:87]
	v_mfma_f32_16x16x32_bf16 v[80:83], v[124:127], v[184:187], v[80:83]
	v_mfma_f32_16x16x32_bf16 v[148:151], v[108:111], v[156:159], v[148:151]
	v_mfma_f32_16x16x32_bf16 v[144:147], v[132:135], v[156:159], v[144:147]
	v_mfma_f32_16x16x32_bf16 v[128:131], v[108:111], v[172:175], v[128:131]
	v_mfma_f32_16x16x32_bf16 v[120:123], v[132:135], v[172:175], v[120:123]
	v_mfma_f32_16x16x32_bf16 v[100:103], v[108:111], v[180:183], v[100:103]
	v_mfma_f32_16x16x32_bf16 v[96:99], v[132:135], v[180:183], v[96:99]
	v_mfma_f32_16x16x32_bf16 v[84:87], v[108:111], v[188:191], v[84:87]
	v_mfma_f32_16x16x32_bf16 v[80:83], v[132:135], v[188:191], v[80:83]
	s_setprio 0
	s_barrier
	s_nop 0
	s_add_i32 s49, s49, s38
	v_lshl_add_u64 v[208:209], s[34:35], 0, v[192:193]
	s_mov_b32 m0, s49
	ds_read_b128 v[152:155], v235 offset:16384
	ds_read_b128 v[156:159], v235 offset:17408
	ds_read_b128 v[168:171], v235 offset:18432
	ds_read_b128 v[172:175], v235 offset:19456
	ds_read_b128 v[176:179], v235 offset:20480
	ds_read_b128 v[180:183], v235 offset:21504
	ds_read_b128 v[184:187], v235 offset:22528
	ds_read_b128 v[188:191], v235 offset:23552
	global_load_lds_dwordx4 v[208:209], off
	s_add_i32 m0, s49, 0x2000
	s_add_u32 s50, s34, 0x40000
	v_lshl_add_u64 v[210:211], s[34:35], 0, v[200:201]
	s_addc_u32 s51, s35, 0
	s_add_i32 s49, s52, s38
	global_load_lds_dwordx4 v[210:211], off
	v_lshl_add_u64 v[212:213], s[50:51], 0, v[192:193]
	s_mov_b32 m0, s49
	v_lshl_add_u64 v[214:215], s[36:37], 0, v[198:199]
	global_load_lds_dwordx4 v[212:213], off
	v_lshl_add_u64 v[212:213], s[50:51], 0, v[200:201]
	s_add_i32 m0, s49, 0x2000
	s_nop 0
	global_load_lds_dwordx4 v[212:213], off
	v_lshl_add_u64 v[212:213], s[36:37], 0, v[196:197]
	s_mov_b32 m0, s39
	s_nop 0
	global_load_lds_dwordx4 v[212:213], off
	s_mov_b32 m0, s40
	s_nop 0
	global_load_lds_dwordx4 v[214:215], off
	s_waitcnt vmcnt(8)
	s_waitcnt lgkmcnt(0)
	s_barrier
	s_setprio 1
	s_waitcnt lgkmcnt(0)
	v_mfma_f32_16x16x32_bf16 v[72:75], v[56:59], v[152:155], v[72:75]
	v_mfma_f32_16x16x32_bf16 v[64:67], v[68:71], v[152:155], v[64:67]
	v_mfma_f32_16x16x32_bf16 v[44:47], v[56:59], v[168:171], v[44:47]
	v_mfma_f32_16x16x32_bf16 v[40:43], v[68:71], v[168:171], v[40:43]
	v_mfma_f32_16x16x32_bf16 v[28:31], v[56:59], v[176:179], v[28:31]
	v_mfma_f32_16x16x32_bf16 v[24:27], v[68:71], v[176:179], v[24:27]
	v_mfma_f32_16x16x32_bf16 v[12:15], v[56:59], v[184:187], v[12:15]
	v_mfma_f32_16x16x32_bf16 v[8:11], v[68:71], v[184:187], v[8:11]
	v_mfma_f32_16x16x32_bf16 v[72:75], v[60:63], v[156:159], v[72:75]
	v_mfma_f32_16x16x32_bf16 v[64:67], v[76:79], v[156:159], v[64:67]
	v_mfma_f32_16x16x32_bf16 v[44:47], v[60:63], v[172:175], v[44:47]
	v_mfma_f32_16x16x32_bf16 v[40:43], v[76:79], v[172:175], v[40:43]
	v_mfma_f32_16x16x32_bf16 v[28:31], v[60:63], v[180:183], v[28:31]
	v_mfma_f32_16x16x32_bf16 v[24:27], v[76:79], v[180:183], v[24:27]
	v_mfma_f32_16x16x32_bf16 v[12:15], v[60:63], v[188:191], v[12:15]
	v_mfma_f32_16x16x32_bf16 v[8:11], v[76:79], v[188:191], v[8:11]
	s_setprio 0
	s_setprio 1
	v_mfma_f32_16x16x32_bf16 v[52:55], v[104:107], v[152:155], v[52:55]
	v_mfma_f32_16x16x32_bf16 v[48:51], v[124:127], v[152:155], v[48:51]
	v_mfma_f32_16x16x32_bf16 v[36:39], v[104:107], v[168:171], v[36:39]
	v_mfma_f32_16x16x32_bf16 v[32:35], v[124:127], v[168:171], v[32:35]
	v_mfma_f32_16x16x32_bf16 v[20:23], v[104:107], v[176:179], v[20:23]
	v_mfma_f32_16x16x32_bf16 v[16:19], v[124:127], v[176:179], v[16:19]
	v_mfma_f32_16x16x32_bf16 v[4:7], v[104:107], v[184:187], v[4:7]
	v_mfma_f32_16x16x32_bf16 v[0:3], v[124:127], v[184:187], v[0:3]
	v_mfma_f32_16x16x32_bf16 v[52:55], v[108:111], v[156:159], v[52:55]
	v_mfma_f32_16x16x32_bf16 v[48:51], v[132:135], v[156:159], v[48:51]
	v_mfma_f32_16x16x32_bf16 v[36:39], v[108:111], v[172:175], v[36:39]
	v_mfma_f32_16x16x32_bf16 v[32:35], v[132:135], v[172:175], v[32:35]
	v_mfma_f32_16x16x32_bf16 v[20:23], v[108:111], v[180:183], v[20:23]
	v_mfma_f32_16x16x32_bf16 v[16:19], v[132:135], v[180:183], v[16:19]
	v_mfma_f32_16x16x32_bf16 v[4:7], v[108:111], v[188:191], v[4:7]
	v_mfma_f32_16x16x32_bf16 v[0:3], v[132:135], v[188:191], v[0:3]
	s_setprio 0
	s_barrier
	s_nop 0
	s_add_i32 s49, 0, 0x18000
	s_add_i32 s50, 0, 0x1c000
	v_add_u32_e32 v76, s49, v233
	v_add_u32_e32 v132, s50, v233
	ds_read_b128 v[56:59], v76
	ds_read_b128 v[60:63], v76 offset:1024
	ds_read_b128 v[68:71], v76 offset:2048
	ds_read_b128 v[76:79], v76 offset:3072
	ds_read_b128 v[104:107], v132
	ds_read_b128 v[108:111], v132 offset:1024
	ds_read_b128 v[124:127], v132 offset:2048
	ds_read_b128 v[132:135], v132 offset:3072
	s_add_u32 s36, s36, 0x40000
	s_addc_u32 s37, s37, 0
	s_mov_b32 m0, s41
	v_lshl_add_u64 v[216:217], s[36:37], 0, v[196:197]
	ds_read_b128 v[152:155], v235 offset:32768
	ds_read_b128 v[156:159], v235 offset:33792
	ds_read_b128 v[168:171], v235 offset:34816
	ds_read_b128 v[172:175], v235 offset:35840
	ds_read_b128 v[176:179], v235 offset:36864
	ds_read_b128 v[180:183], v235 offset:37888
	ds_read_b128 v[184:187], v235 offset:38912
	ds_read_b128 v[188:191], v235 offset:39936
	global_load_lds_dwordx4 v[216:217], off
	v_lshl_add_u64 v[216:217], s[36:37], 0, v[198:199]
	s_mov_b32 m0, s42
	s_nop 0
	global_load_lds_dwordx4 v[216:217], off
	s_waitcnt vmcnt(8)
	s_waitcnt lgkmcnt(0)
	s_barrier
	s_setprio 1
	s_waitcnt lgkmcnt(0)
	v_mfma_f32_16x16x32_bf16 v[164:167], v[56:59], v[152:155], v[164:167]
	v_mfma_f32_16x16x32_bf16 v[160:163], v[68:71], v[152:155], v[160:163]
	v_mfma_f32_16x16x32_bf16 v[140:143], v[56:59], v[168:171], v[140:143]
	v_mfma_f32_16x16x32_bf16 v[136:139], v[68:71], v[168:171], v[136:139]
	v_mfma_f32_16x16x32_bf16 v[116:119], v[56:59], v[176:179], v[116:119]
	v_mfma_f32_16x16x32_bf16 v[112:115], v[68:71], v[176:179], v[112:115]
	v_mfma_f32_16x16x32_bf16 v[92:95], v[56:59], v[184:187], v[92:95]
	v_mfma_f32_16x16x32_bf16 v[88:91], v[68:71], v[184:187], v[88:91]
	v_mfma_f32_16x16x32_bf16 v[164:167], v[60:63], v[156:159], v[164:167]
	v_mfma_f32_16x16x32_bf16 v[160:163], v[76:79], v[156:159], v[160:163]
	v_mfma_f32_16x16x32_bf16 v[140:143], v[60:63], v[172:175], v[140:143]
	v_mfma_f32_16x16x32_bf16 v[136:139], v[76:79], v[172:175], v[136:139]
	v_mfma_f32_16x16x32_bf16 v[116:119], v[60:63], v[180:183], v[116:119]
	v_mfma_f32_16x16x32_bf16 v[112:115], v[76:79], v[180:183], v[112:115]
	v_mfma_f32_16x16x32_bf16 v[92:95], v[60:63], v[188:191], v[92:95]
	v_mfma_f32_16x16x32_bf16 v[88:91], v[76:79], v[188:191], v[88:91]
	s_setprio 0
	s_setprio 1
	v_mfma_f32_16x16x32_bf16 v[148:151], v[104:107], v[152:155], v[148:151]
	v_mfma_f32_16x16x32_bf16 v[144:147], v[124:127], v[152:155], v[144:147]
	v_mfma_f32_16x16x32_bf16 v[128:131], v[104:107], v[168:171], v[128:131]
	v_mfma_f32_16x16x32_bf16 v[120:123], v[124:127], v[168:171], v[120:123]
	v_mfma_f32_16x16x32_bf16 v[100:103], v[104:107], v[176:179], v[100:103]
	v_mfma_f32_16x16x32_bf16 v[96:99], v[124:127], v[176:179], v[96:99]
	v_mfma_f32_16x16x32_bf16 v[84:87], v[104:107], v[184:187], v[84:87]
	v_mfma_f32_16x16x32_bf16 v[80:83], v[124:127], v[184:187], v[80:83]
	v_mfma_f32_16x16x32_bf16 v[148:151], v[108:111], v[156:159], v[148:151]
	v_mfma_f32_16x16x32_bf16 v[144:147], v[132:135], v[156:159], v[144:147]
	v_mfma_f32_16x16x32_bf16 v[128:131], v[108:111], v[172:175], v[128:131]
	v_mfma_f32_16x16x32_bf16 v[120:123], v[132:135], v[172:175], v[120:123]
	v_mfma_f32_16x16x32_bf16 v[100:103], v[108:111], v[180:183], v[100:103]
	v_mfma_f32_16x16x32_bf16 v[96:99], v[132:135], v[180:183], v[96:99]
	v_mfma_f32_16x16x32_bf16 v[84:87], v[108:111], v[188:191], v[84:87]
	v_mfma_f32_16x16x32_bf16 v[80:83], v[132:135], v[188:191], v[80:83]
	s_setprio 0
	s_barrier
	s_add_i32 s36, s49, s38
	v_lshl_add_u64 v[208:209], v[208:209], 0, s[2:3]
	s_mov_b32 m0, s36
	ds_read_b128 v[152:155], v235 offset:49152
	ds_read_b128 v[156:159], v235 offset:50176
	ds_read_b128 v[168:171], v235 offset:51200
	ds_read_b128 v[172:175], v235 offset:52224
	ds_read_b128 v[176:179], v235 offset:53248
	ds_read_b128 v[180:183], v235 offset:54272
	ds_read_b128 v[184:187], v235 offset:55296
	ds_read_b128 v[188:191], v235 offset:56320
	global_load_lds_dwordx4 v[208:209], off
	s_add_i32 m0, s36, 0x2000
	s_add_u32 s34, s34, 0x40080
	v_lshl_add_u64 v[208:209], v[210:211], 0, s[2:3]
	s_addc_u32 s35, s35, 0
	s_add_i32 s36, s50, s38
	global_load_lds_dwordx4 v[208:209], off
	v_lshl_add_u64 v[208:209], s[34:35], 0, v[192:193]
	s_mov_b32 m0, s36
	s_nop 0
	global_load_lds_dwordx4 v[208:209], off
	v_lshl_add_u64 v[208:209], s[34:35], 0, v[200:201]
	s_add_i32 m0, s36, 0x2000
	s_nop 0
	global_load_lds_dwordx4 v[208:209], off
	v_lshl_add_u64 v[208:209], v[212:213], 0, s[2:3]
	s_mov_b32 m0, s43
	s_nop 0
	global_load_lds_dwordx4 v[208:209], off
	v_lshl_add_u64 v[208:209], v[214:215], 0, s[2:3]
	s_mov_b32 m0, s44
	s_nop 0
	global_load_lds_dwordx4 v[208:209], off
	s_waitcnt vmcnt(8)
	s_waitcnt lgkmcnt(0)
	s_barrier
	s_setprio 1
	s_waitcnt lgkmcnt(0)
	v_mfma_f32_16x16x32_bf16 v[72:75], v[56:59], v[152:155], v[72:75]
	v_mfma_f32_16x16x32_bf16 v[64:67], v[68:71], v[152:155], v[64:67]
	v_mfma_f32_16x16x32_bf16 v[44:47], v[56:59], v[168:171], v[44:47]
	v_mfma_f32_16x16x32_bf16 v[40:43], v[68:71], v[168:171], v[40:43]
	v_mfma_f32_16x16x32_bf16 v[28:31], v[56:59], v[176:179], v[28:31]
	v_mfma_f32_16x16x32_bf16 v[24:27], v[68:71], v[176:179], v[24:27]
	v_mfma_f32_16x16x32_bf16 v[12:15], v[56:59], v[184:187], v[12:15]
	v_mfma_f32_16x16x32_bf16 v[8:11], v[68:71], v[184:187], v[8:11]
	v_mfma_f32_16x16x32_bf16 v[72:75], v[60:63], v[156:159], v[72:75]
	v_mfma_f32_16x16x32_bf16 v[64:67], v[76:79], v[156:159], v[64:67]
	v_mfma_f32_16x16x32_bf16 v[44:47], v[60:63], v[172:175], v[44:47]
	v_mfma_f32_16x16x32_bf16 v[40:43], v[76:79], v[172:175], v[40:43]
	v_mfma_f32_16x16x32_bf16 v[28:31], v[60:63], v[180:183], v[28:31]
	v_mfma_f32_16x16x32_bf16 v[24:27], v[76:79], v[180:183], v[24:27]
	v_mfma_f32_16x16x32_bf16 v[12:15], v[60:63], v[188:191], v[12:15]
	v_mfma_f32_16x16x32_bf16 v[8:11], v[76:79], v[188:191], v[8:11]
	s_setprio 0
	s_setprio 1
	v_mfma_f32_16x16x32_bf16 v[52:55], v[104:107], v[152:155], v[52:55]
	v_mfma_f32_16x16x32_bf16 v[48:51], v[124:127], v[152:155], v[48:51]
	v_mfma_f32_16x16x32_bf16 v[36:39], v[104:107], v[168:171], v[36:39]
	v_mfma_f32_16x16x32_bf16 v[32:35], v[124:127], v[168:171], v[32:35]
	v_mfma_f32_16x16x32_bf16 v[20:23], v[104:107], v[176:179], v[20:23]
	v_mfma_f32_16x16x32_bf16 v[16:19], v[124:127], v[176:179], v[16:19]
	v_mfma_f32_16x16x32_bf16 v[4:7], v[104:107], v[184:187], v[4:7]
	v_mfma_f32_16x16x32_bf16 v[0:3], v[124:127], v[184:187], v[0:3]
	v_mfma_f32_16x16x32_bf16 v[52:55], v[108:111], v[156:159], v[52:55]
	v_mfma_f32_16x16x32_bf16 v[48:51], v[132:135], v[156:159], v[48:51]
	v_mfma_f32_16x16x32_bf16 v[36:39], v[108:111], v[172:175], v[36:39]
	v_mfma_f32_16x16x32_bf16 v[32:35], v[132:135], v[172:175], v[32:35]
	v_mfma_f32_16x16x32_bf16 v[20:23], v[108:111], v[180:183], v[20:23]
	v_mfma_f32_16x16x32_bf16 v[16:19], v[132:135], v[180:183], v[16:19]
	v_mfma_f32_16x16x32_bf16 v[4:7], v[108:111], v[188:191], v[4:7]
	v_mfma_f32_16x16x32_bf16 v[0:3], v[132:135], v[188:191], v[0:3]
	s_setprio 0
	s_barrier
	s_add_i32 s48, s48, 2
	s_add_u32 s46, s46, 0x100
	s_addc_u32 s47, s47, 0
	s_add_u32 s8, s8, 0x100
	s_addc_u32 s9, s9, 0
	s_cmp_gt_u32 s48, 13
	s_cbranch_scc0 .LBB0_124
	s_and_b64 vcc, exec, s[16:17]
	s_cbranch_vccz .LBB0_127
	s_barrier

.LBB0_574:
	s_nop 0
	s_add_u32 s34, s30, 0xfffc0080
	s_addc_u32 s35, s31, -1
	s_add_i32 s54, 0, 0x10000
	s_cmp_eq_u32 s53, 12
	s_cselect_b32 s37, s25, s35
	s_cselect_b32 s36, s49, s34
	v_add_u32_e32 v138, s54, v141
	s_cselect_b32 s35, s23, s52
	s_cselect_b32 s34, s50, s51
	s_add_i32 s61, 0, 0x14000
	ds_read_b128 v[144:147], v138
	ds_read_b128 v[148:151], v138 offset:1024
	ds_read_b128 v[152:155], v138 offset:2048
	ds_read_b128 v[156:159], v138 offset:3072
	v_add_u32_e32 v138, s61, v141
	ds_read_b128 v[160:163], v138
	ds_read_b128 v[164:167], v138 offset:1024
	ds_read_b128 v[168:171], v138 offset:2048
	ds_read_b128 v[172:175], v138 offset:3072
	s_add_i32 m0, s40, 0xc000
	ds_read_b128 v[176:179], v143
	ds_read_b128 v[180:183], v143 offset:1024
	ds_read_b128 v[184:187], v143 offset:2048
	ds_read_b128 v[188:191], v143 offset:3072
	ds_read_b128 v[196:199], v143 offset:4096
	ds_read_b128 v[200:203], v143 offset:5120
	ds_read_b128 v[204:207], v143 offset:6144
	ds_read_b128 v[208:211], v143 offset:7168
	global_load_lds_dwordx4 v136, s[30:31]
	s_add_i32 m0, s40, 0xe000
	s_nop 0
	global_load_lds_dwordx4 v134, s[30:31]
	s_waitcnt vmcnt(8)
	s_waitcnt lgkmcnt(0)
	s_barrier
	s_setprio 1
	s_waitcnt lgkmcnt(0)
	v_mfma_f32_16x16x32_bf16 v[124:127], v[144:147], v[176:179], v[124:127]
	v_mfma_f32_16x16x32_bf16 v[120:123], v[152:155], v[176:179], v[120:123]
	v_mfma_f32_16x16x32_bf16 v[108:111], v[144:147], v[184:187], v[108:111]
	v_mfma_f32_16x16x32_bf16 v[104:107], v[152:155], v[184:187], v[104:107]
	v_mfma_f32_16x16x32_bf16 v[92:95], v[144:147], v[196:199], v[92:95]
	v_mfma_f32_16x16x32_bf16 v[88:91], v[152:155], v[196:199], v[88:91]
	v_mfma_f32_16x16x32_bf16 v[76:79], v[144:147], v[204:207], v[76:79]
	v_mfma_f32_16x16x32_bf16 v[72:75], v[152:155], v[204:207], v[72:75]
	v_mfma_f32_16x16x32_bf16 v[124:127], v[148:151], v[180:183], v[124:127]
	v_mfma_f32_16x16x32_bf16 v[120:123], v[156:159], v[180:183], v[120:123]
	v_mfma_f32_16x16x32_bf16 v[108:111], v[148:151], v[188:191], v[108:111]
	v_mfma_f32_16x16x32_bf16 v[104:107], v[156:159], v[188:191], v[104:107]
	v_mfma_f32_16x16x32_bf16 v[92:95], v[148:151], v[200:203], v[92:95]
	v_mfma_f32_16x16x32_bf16 v[88:91], v[156:159], v[200:203], v[88:91]
	v_mfma_f32_16x16x32_bf16 v[76:79], v[148:151], v[208:211], v[76:79]
	v_mfma_f32_16x16x32_bf16 v[72:75], v[156:159], v[208:211], v[72:75]
	s_setprio 0
	s_setprio 1
	v_mfma_f32_16x16x32_bf16 v[116:119], v[160:163], v[176:179], v[116:119]
	v_mfma_f32_16x16x32_bf16 v[112:115], v[168:171], v[176:179], v[112:115]
	v_mfma_f32_16x16x32_bf16 v[100:103], v[160:163], v[184:187], v[100:103]
	v_mfma_f32_16x16x32_bf16 v[96:99], v[168:171], v[184:187], v[96:99]
	v_mfma_f32_16x16x32_bf16 v[84:87], v[160:163], v[196:199], v[84:87]
	v_mfma_f32_16x16x32_bf16 v[80:83], v[168:171], v[196:199], v[80:83]
	v_mfma_f32_16x16x32_bf16 v[68:71], v[160:163], v[204:207], v[68:71]
	v_mfma_f32_16x16x32_bf16 v[64:67], v[168:171], v[204:207], v[64:67]
	v_mfma_f32_16x16x32_bf16 v[116:119], v[164:167], v[180:183], v[116:119]
	v_mfma_f32_16x16x32_bf16 v[112:115], v[172:175], v[180:183], v[112:115]
	v_mfma_f32_16x16x32_bf16 v[100:103], v[164:167], v[188:191], v[100:103]
	v_mfma_f32_16x16x32_bf16 v[96:99], v[172:175], v[188:191], v[96:99]
	v_mfma_f32_16x16x32_bf16 v[84:87], v[164:167], v[200:203], v[84:87]
	v_mfma_f32_16x16x32_bf16 v[80:83], v[172:175], v[200:203], v[80:83]
	v_mfma_f32_16x16x32_bf16 v[68:71], v[164:167], v[208:211], v[68:71]
	v_mfma_f32_16x16x32_bf16 v[64:67], v[172:175], v[208:211], v[64:67]
	s_setprio 0
	s_barrier
	s_add_i32 s54, s54, s39
	s_mov_b32 m0, s54
	ds_read_b128 v[176:179], v143 offset:16384
	ds_read_b128 v[180:183], v143 offset:17408
	ds_read_b128 v[184:187], v143 offset:18432
	ds_read_b128 v[188:191], v143 offset:19456
	ds_read_b128 v[196:199], v143 offset:20480
	ds_read_b128 v[200:203], v143 offset:21504
	ds_read_b128 v[204:207], v143 offset:22528
	ds_read_b128 v[208:211], v143 offset:23552
	global_load_lds_dwordx4 v192, s[34:35]
	s_add_i32 m0, s54, 0x2000
	s_add_u32 s54, s34, 0x40000
	s_addc_u32 s55, s35, 0
	s_add_i32 s61, s61, s39
	global_load_lds_dwordx4 v128, s[34:35]
	s_mov_b32 m0, s61
	s_nop 0
	global_load_lds_dwordx4 v192, s[54:55]
	s_add_i32 m0, s61, 0x2000
	s_nop 0
	global_load_lds_dwordx4 v128, s[54:55]
	s_mov_b32 m0, s40
	s_nop 0
	global_load_lds_dwordx4 v132, s[36:37]
	s_mov_b32 m0, s41
	s_nop 0
	global_load_lds_dwordx4 v130, s[36:37]
	s_waitcnt vmcnt(8)
	s_waitcnt lgkmcnt(0)
	s_barrier
	s_setprio 1
	s_waitcnt lgkmcnt(0)
	v_mfma_f32_16x16x32_bf16 v[60:63], v[144:147], v[176:179], v[60:63]
	v_mfma_f32_16x16x32_bf16 v[56:59], v[152:155], v[176:179], v[56:59]
	v_mfma_f32_16x16x32_bf16 v[44:47], v[144:147], v[184:187], v[44:47]
	v_mfma_f32_16x16x32_bf16 v[40:43], v[152:155], v[184:187], v[40:43]
	v_mfma_f32_16x16x32_bf16 v[28:31], v[144:147], v[196:199], v[28:31]
	v_mfma_f32_16x16x32_bf16 v[24:27], v[152:155], v[196:199], v[24:27]
	v_mfma_f32_16x16x32_bf16 v[12:15], v[144:147], v[204:207], v[12:15]
	v_mfma_f32_16x16x32_bf16 v[8:11], v[152:155], v[204:207], v[8:11]
	v_mfma_f32_16x16x32_bf16 v[60:63], v[148:151], v[180:183], v[60:63]
	v_mfma_f32_16x16x32_bf16 v[56:59], v[156:159], v[180:183], v[56:59]
	v_mfma_f32_16x16x32_bf16 v[44:47], v[148:151], v[188:191], v[44:47]
	v_mfma_f32_16x16x32_bf16 v[40:43], v[156:159], v[188:191], v[40:43]
	v_mfma_f32_16x16x32_bf16 v[28:31], v[148:151], v[200:203], v[28:31]
	v_mfma_f32_16x16x32_bf16 v[24:27], v[156:159], v[200:203], v[24:27]
	v_mfma_f32_16x16x32_bf16 v[12:15], v[148:151], v[208:211], v[12:15]
	v_mfma_f32_16x16x32_bf16 v[8:11], v[156:159], v[208:211], v[8:11]
	s_setprio 0
	s_setprio 1
	v_mfma_f32_16x16x32_bf16 v[52:55], v[160:163], v[176:179], v[52:55]
	v_mfma_f32_16x16x32_bf16 v[48:51], v[168:171], v[176:179], v[48:51]
	v_mfma_f32_16x16x32_bf16 v[36:39], v[160:163], v[184:187], v[36:39]
	v_mfma_f32_16x16x32_bf16 v[32:35], v[168:171], v[184:187], v[32:35]
	v_mfma_f32_16x16x32_bf16 v[20:23], v[160:163], v[196:199], v[20:23]
	v_mfma_f32_16x16x32_bf16 v[16:19], v[168:171], v[196:199], v[16:19]
	v_mfma_f32_16x16x32_bf16 v[4:7], v[160:163], v[204:207], v[4:7]
	v_mfma_f32_16x16x32_bf16 v[0:3], v[168:171], v[204:207], v[0:3]
	v_mfma_f32_16x16x32_bf16 v[52:55], v[164:167], v[180:183], v[52:55]
	v_mfma_f32_16x16x32_bf16 v[48:51], v[172:175], v[180:183], v[48:51]
	v_mfma_f32_16x16x32_bf16 v[36:39], v[164:167], v[188:191], v[36:39]
	v_mfma_f32_16x16x32_bf16 v[32:35], v[172:175], v[188:191], v[32:35]
	v_mfma_f32_16x16x32_bf16 v[20:23], v[164:167], v[200:203], v[20:23]
	v_mfma_f32_16x16x32_bf16 v[16:19], v[172:175], v[200:203], v[16:19]
	v_mfma_f32_16x16x32_bf16 v[4:7], v[164:167], v[208:211], v[4:7]
	v_mfma_f32_16x16x32_bf16 v[0:3], v[172:175], v[208:211], v[0:3]
	s_setprio 0
	s_barrier
	s_nop 0
	s_add_i32 s54, 0, 0x18000
	s_add_i32 s55, 0, 0x1c000
	v_add_u32_e32 v156, s54, v141
	v_add_u32_e32 v172, s55, v141
	ds_read_b128 v[144:147], v156
	ds_read_b128 v[148:151], v156 offset:1024
	ds_read_b128 v[152:155], v156 offset:2048
	ds_read_b128 v[156:159], v156 offset:3072
	ds_read_b128 v[160:163], v172
	ds_read_b128 v[164:167], v172 offset:1024
	ds_read_b128 v[168:171], v172 offset:2048
	ds_read_b128 v[172:175], v172 offset:3072
	s_add_u32 s36, s36, 0x40000
	s_addc_u32 s37, s37, 0
	s_mov_b32 m0, s42
	ds_read_b128 v[176:179], v143 offset:32768
	ds_read_b128 v[180:183], v143 offset:33792
	ds_read_b128 v[184:187], v143 offset:34816
	ds_read_b128 v[188:191], v143 offset:35840
	ds_read_b128 v[196:199], v143 offset:36864
	ds_read_b128 v[200:203], v143 offset:37888
	ds_read_b128 v[204:207], v143 offset:38912
	ds_read_b128 v[208:211], v143 offset:39936
	global_load_lds_dwordx4 v132, s[36:37]
	s_mov_b32 m0, s43
	s_nop 0
	global_load_lds_dwordx4 v130, s[36:37]
	s_waitcnt vmcnt(8)
	s_waitcnt lgkmcnt(0)
	s_barrier
	s_setprio 1
	s_waitcnt lgkmcnt(0)
	v_mfma_f32_16x16x32_bf16 v[124:127], v[144:147], v[176:179], v[124:127]
	v_mfma_f32_16x16x32_bf16 v[120:123], v[152:155], v[176:179], v[120:123]
	v_mfma_f32_16x16x32_bf16 v[108:111], v[144:147], v[184:187], v[108:111]
	v_mfma_f32_16x16x32_bf16 v[104:107], v[152:155], v[184:187], v[104:107]
	v_mfma_f32_16x16x32_bf16 v[92:95], v[144:147], v[196:199], v[92:95]
	v_mfma_f32_16x16x32_bf16 v[88:91], v[152:155], v[196:199], v[88:91]
	v_mfma_f32_16x16x32_bf16 v[76:79], v[144:147], v[204:207], v[76:79]
	v_mfma_f32_16x16x32_bf16 v[72:75], v[152:155], v[204:207], v[72:75]
	v_mfma_f32_16x16x32_bf16 v[124:127], v[148:151], v[180:183], v[124:127]
	v_mfma_f32_16x16x32_bf16 v[120:123], v[156:159], v[180:183], v[120:123]
	v_mfma_f32_16x16x32_bf16 v[108:111], v[148:151], v[188:191], v[108:111]
	v_mfma_f32_16x16x32_bf16 v[104:107], v[156:159], v[188:191], v[104:107]
	v_mfma_f32_16x16x32_bf16 v[92:95], v[148:151], v[200:203], v[92:95]
	v_mfma_f32_16x16x32_bf16 v[88:91], v[156:159], v[200:203], v[88:91]
	v_mfma_f32_16x16x32_bf16 v[76:79], v[148:151], v[208:211], v[76:79]
	v_mfma_f32_16x16x32_bf16 v[72:75], v[156:159], v[208:211], v[72:75]
	s_setprio 0
	s_setprio 1
	v_mfma_f32_16x16x32_bf16 v[116:119], v[160:163], v[176:179], v[116:119]
	v_mfma_f32_16x16x32_bf16 v[112:115], v[168:171], v[176:179], v[112:115]
	v_mfma_f32_16x16x32_bf16 v[100:103], v[160:163], v[184:187], v[100:103]
	v_mfma_f32_16x16x32_bf16 v[96:99], v[168:171], v[184:187], v[96:99]
	v_mfma_f32_16x16x32_bf16 v[84:87], v[160:163], v[196:199], v[84:87]
	v_mfma_f32_16x16x32_bf16 v[80:83], v[168:171], v[196:199], v[80:83]
	v_mfma_f32_16x16x32_bf16 v[68:71], v[160:163], v[204:207], v[68:71]
	v_mfma_f32_16x16x32_bf16 v[64:67], v[168:171], v[204:207], v[64:67]
	v_mfma_f32_16x16x32_bf16 v[116:119], v[164:167], v[180:183], v[116:119]
	v_mfma_f32_16x16x32_bf16 v[112:115], v[172:175], v[180:183], v[112:115]
	v_mfma_f32_16x16x32_bf16 v[100:103], v[164:167], v[188:191], v[100:103]
	v_mfma_f32_16x16x32_bf16 v[96:99], v[172:175], v[188:191], v[96:99]
	v_mfma_f32_16x16x32_bf16 v[84:87], v[164:167], v[200:203], v[84:87]
	v_mfma_f32_16x16x32_bf16 v[80:83], v[172:175], v[200:203], v[80:83]
	v_mfma_f32_16x16x32_bf16 v[68:71], v[164:167], v[208:211], v[68:71]
	v_mfma_f32_16x16x32_bf16 v[64:67], v[172:175], v[208:211], v[64:67]
	s_setprio 0
	s_barrier
	s_nop 0
	s_add_u32 s36, s36, 0xfffc0080
	s_addc_u32 s37, s37, -1
	s_add_u32 s34, s34, 0x80
	s_addc_u32 s35, s35, 0
	s_add_i32 m0, s54, s39
	ds_read_b128 v[176:179], v143 offset:49152
	ds_read_b128 v[180:183], v143 offset:50176
	ds_read_b128 v[184:187], v143 offset:51200
	ds_read_b128 v[188:191], v143 offset:52224
	ds_read_b128 v[196:199], v143 offset:53248
	ds_read_b128 v[200:203], v143 offset:54272
	ds_read_b128 v[204:207], v143 offset:55296
	ds_read_b128 v[208:211], v143 offset:56320
	global_load_lds_dwordx4 v192, s[34:35]
	s_add_i32 m0, m0, 0x2000
	s_nop 0
	global_load_lds_dwordx4 v128, s[34:35]
	s_add_u32 s34, s34, 0x40000
	s_addc_u32 s35, s35, 0
	s_add_i32 m0, s55, s39
	s_nop 0
	global_load_lds_dwordx4 v192, s[34:35]
	s_add_i32 m0, m0, 0x2000
	s_nop 0
	global_load_lds_dwordx4 v128, s[34:35]
	s_mov_b32 m0, s44
	s_nop 0
	global_load_lds_dwordx4 v132, s[36:37]
	s_mov_b32 m0, s45
	s_nop 0
	global_load_lds_dwordx4 v130, s[36:37]
	s_waitcnt vmcnt(8)
	s_waitcnt lgkmcnt(0)
	s_barrier
	s_setprio 1
	s_waitcnt lgkmcnt(0)
	v_mfma_f32_16x16x32_bf16 v[60:63], v[144:147], v[176:179], v[60:63]
	v_mfma_f32_16x16x32_bf16 v[56:59], v[152:155], v[176:179], v[56:59]
	v_mfma_f32_16x16x32_bf16 v[44:47], v[144:147], v[184:187], v[44:47]
	v_mfma_f32_16x16x32_bf16 v[40:43], v[152:155], v[184:187], v[40:43]
	v_mfma_f32_16x16x32_bf16 v[28:31], v[144:147], v[196:199], v[28:31]
	v_mfma_f32_16x16x32_bf16 v[24:27], v[152:155], v[196:199], v[24:27]
	v_mfma_f32_16x16x32_bf16 v[12:15], v[144:147], v[204:207], v[12:15]
	v_mfma_f32_16x16x32_bf16 v[8:11], v[152:155], v[204:207], v[8:11]
	v_mfma_f32_16x16x32_bf16 v[60:63], v[148:151], v[180:183], v[60:63]
	v_mfma_f32_16x16x32_bf16 v[56:59], v[156:159], v[180:183], v[56:59]
	v_mfma_f32_16x16x32_bf16 v[44:47], v[148:151], v[188:191], v[44:47]
	v_mfma_f32_16x16x32_bf16 v[40:43], v[156:159], v[188:191], v[40:43]
	v_mfma_f32_16x16x32_bf16 v[28:31], v[148:151], v[200:203], v[28:31]
	v_mfma_f32_16x16x32_bf16 v[24:27], v[156:159], v[200:203], v[24:27]
	v_mfma_f32_16x16x32_bf16 v[12:15], v[148:151], v[208:211], v[12:15]
	v_mfma_f32_16x16x32_bf16 v[8:11], v[156:159], v[208:211], v[8:11]
	s_setprio 0
	s_setprio 1
	v_mfma_f32_16x16x32_bf16 v[52:55], v[160:163], v[176:179], v[52:55]
	v_mfma_f32_16x16x32_bf16 v[48:51], v[168:171], v[176:179], v[48:51]
	v_mfma_f32_16x16x32_bf16 v[36:39], v[160:163], v[184:187], v[36:39]
	v_mfma_f32_16x16x32_bf16 v[32:35], v[168:171], v[184:187], v[32:35]
	v_mfma_f32_16x16x32_bf16 v[20:23], v[160:163], v[196:199], v[20:23]
	v_mfma_f32_16x16x32_bf16 v[16:19], v[168:171], v[196:199], v[16:19]
	v_mfma_f32_16x16x32_bf16 v[4:7], v[160:163], v[204:207], v[4:7]
	v_mfma_f32_16x16x32_bf16 v[0:3], v[168:171], v[204:207], v[0:3]
	v_mfma_f32_16x16x32_bf16 v[52:55], v[164:167], v[180:183], v[52:55]
	v_mfma_f32_16x16x32_bf16 v[48:51], v[172:175], v[180:183], v[48:51]
	v_mfma_f32_16x16x32_bf16 v[36:39], v[164:167], v[188:191], v[36:39]
	v_mfma_f32_16x16x32_bf16 v[32:35], v[172:175], v[188:191], v[32:35]
	v_mfma_f32_16x16x32_bf16 v[20:23], v[164:167], v[200:203], v[20:23]
	v_mfma_f32_16x16x32_bf16 v[16:19], v[172:175], v[200:203], v[16:19]
	v_mfma_f32_16x16x32_bf16 v[4:7], v[164:167], v[208:211], v[4:7]
	v_mfma_f32_16x16x32_bf16 v[0:3], v[172:175], v[208:211], v[0:3]
	s_setprio 0
	s_barrier
	s_add_i32 s53, s53, 2
	s_add_u32 s51, s51, 0x100
	s_addc_u32 s52, s52, 0
	s_add_u32 s30, s30, 0x100
	s_addc_u32 s31, s31, 0
	s_cmp_gt_u32 s53, 13
	s_cbranch_scc0 .LBB0_574
	s_and_b64 vcc, exec, s[20:21]
	s_cbranch_vccz .LBB0_577
	s_barrier

.LBB0_668:
	s_nop 0
	s_add_i32 s54, s52, 2
	s_add_u32 s55, s12, 0x80
	s_addc_u32 s53, s13, 0
	s_add_i32 s75, 0, 0x10000
	s_cmp_eq_u32 s73, s52
	s_cselect_b32 s53, s47, s53
	s_cselect_b32 s52, s46, s55
	s_cselect_b32 s83, s49, s74
	s_cselect_b32 s82, s48, s51
	s_add_i32 s55, 0, 0x14000
	v_add_u32_e32 v140, s75, v203
	v_add_u32_e32 v156, s55, v203
	ds_read_b128 v[128:131], v140
	ds_read_b128 v[132:135], v140 offset:1024
	ds_read_b128 v[136:139], v140 offset:2048
	ds_read_b128 v[140:143], v140 offset:3072
	ds_read_b128 v[144:147], v156
	ds_read_b128 v[148:151], v156 offset:1024
	ds_read_b128 v[152:155], v156 offset:2048
	ds_read_b128 v[156:159], v156 offset:3072
	v_lshl_add_u64 v[190:191], s[12:13], 0, v[184:185]
	s_add_i32 m0, s63, 0xc000
	ds_read_b128 v[160:163], v231
	ds_read_b128 v[164:167], v231 offset:1024
	ds_read_b128 v[168:171], v231 offset:2048
	ds_read_b128 v[172:175], v231 offset:3072
	ds_read_b128 v[186:189], v231 offset:4096
	ds_read_b128 v[196:199], v231 offset:5120
	ds_read_b128 v[224:227], v231 offset:6144
	ds_read_b128 v[238:241], v231 offset:7168
	global_load_lds_dwordx4 v[190:191], off
	v_lshl_add_u64 v[190:191], s[12:13], 0, v[182:183]
	s_add_i32 m0, s63, 0xe000
	s_nop 0
	global_load_lds_dwordx4 v[190:191], off
	s_waitcnt vmcnt(8)
	s_waitcnt lgkmcnt(0)
	s_barrier
	s_setprio 1
	s_waitcnt lgkmcnt(0)
	v_mfma_f32_16x16x32_bf16 v[68:71], v[128:131], v[160:163], v[68:71]
	v_mfma_f32_16x16x32_bf16 v[72:75], v[136:139], v[160:163], v[72:75]
	v_mfma_f32_16x16x32_bf16 v[8:11], v[128:131], v[168:171], v[8:11]
	v_mfma_f32_16x16x32_bf16 v[16:19], v[136:139], v[168:171], v[16:19]
	v_mfma_f32_16x16x32_bf16 v[56:59], v[128:131], v[186:189], v[56:59]
	v_mfma_f32_16x16x32_bf16 v[60:63], v[136:139], v[186:189], v[60:63]
	v_mfma_f32_16x16x32_bf16 v[36:39], v[128:131], v[224:227], v[36:39]
	v_mfma_f32_16x16x32_bf16 v[44:47], v[136:139], v[224:227], v[44:47]
	v_mfma_f32_16x16x32_bf16 v[68:71], v[132:135], v[164:167], v[68:71]
	v_mfma_f32_16x16x32_bf16 v[72:75], v[140:143], v[164:167], v[72:75]
	v_mfma_f32_16x16x32_bf16 v[8:11], v[132:135], v[172:175], v[8:11]
	v_mfma_f32_16x16x32_bf16 v[16:19], v[140:143], v[172:175], v[16:19]
	v_mfma_f32_16x16x32_bf16 v[56:59], v[132:135], v[196:199], v[56:59]
	v_mfma_f32_16x16x32_bf16 v[60:63], v[140:143], v[196:199], v[60:63]
	v_mfma_f32_16x16x32_bf16 v[36:39], v[132:135], v[238:241], v[36:39]
	v_mfma_f32_16x16x32_bf16 v[44:47], v[140:143], v[238:241], v[44:47]
	s_setprio 0
	s_setprio 1
	v_mfma_f32_16x16x32_bf16 v[12:15], v[144:147], v[160:163], v[12:15]
	v_mfma_f32_16x16x32_bf16 v[20:23], v[152:155], v[160:163], v[20:23]
	v_mfma_f32_16x16x32_bf16 v[0:3], v[144:147], v[168:171], v[0:3]
	v_mfma_f32_16x16x32_bf16 v[4:7], v[152:155], v[168:171], v[4:7]
	v_mfma_f32_16x16x32_bf16 v[32:35], v[144:147], v[186:189], v[32:35]
	v_mfma_f32_16x16x32_bf16 v[40:43], v[152:155], v[186:189], v[40:43]
	v_mfma_f32_16x16x32_bf16 v[24:27], v[144:147], v[224:227], v[24:27]
	v_mfma_f32_16x16x32_bf16 v[28:31], v[152:155], v[224:227], v[28:31]
	v_mfma_f32_16x16x32_bf16 v[12:15], v[148:151], v[164:167], v[12:15]
	v_mfma_f32_16x16x32_bf16 v[20:23], v[156:159], v[164:167], v[20:23]
	v_mfma_f32_16x16x32_bf16 v[0:3], v[148:151], v[172:175], v[0:3]
	v_mfma_f32_16x16x32_bf16 v[4:7], v[156:159], v[172:175], v[4:7]
	v_mfma_f32_16x16x32_bf16 v[32:35], v[148:151], v[196:199], v[32:35]
	v_mfma_f32_16x16x32_bf16 v[40:43], v[156:159], v[196:199], v[40:43]
	v_mfma_f32_16x16x32_bf16 v[24:27], v[148:151], v[238:241], v[24:27]
	v_mfma_f32_16x16x32_bf16 v[28:31], v[156:159], v[238:241], v[28:31]
	s_setprio 0
	s_barrier
	s_add_i32 s75, s75, s62
	v_lshl_add_u64 v[190:191], s[82:83], 0, v[192:193]
	s_mov_b32 m0, s75
	ds_read_b128 v[160:163], v231 offset:16384
	ds_read_b128 v[164:167], v231 offset:17408
	ds_read_b128 v[168:171], v231 offset:18432
	ds_read_b128 v[172:175], v231 offset:19456
	ds_read_b128 v[186:189], v231 offset:20480
	ds_read_b128 v[196:199], v231 offset:21504
	ds_read_b128 v[224:227], v231 offset:22528
	ds_read_b128 v[238:241], v231 offset:23552
	global_load_lds_dwordx4 v[190:191], off
	s_add_i32 m0, s75, 0x2000
	v_lshl_add_u64 v[200:201], s[82:83], 0, v[176:177]
	s_add_u32 s82, s82, s80
	s_addc_u32 s83, s83, 0
	s_add_i32 s55, s55, s62
	global_load_lds_dwordx4 v[200:201], off
	v_lshl_add_u64 v[234:235], s[82:83], 0, v[192:193]
	s_mov_b32 m0, s55
	v_lshl_add_u64 v[242:243], s[82:83], 0, v[176:177]
	global_load_lds_dwordx4 v[234:235], off
	s_add_i32 m0, s55, 0x2000
	v_lshl_add_u64 v[244:245], s[52:53], 0, v[180:181]
	global_load_lds_dwordx4 v[242:243], off
	s_mov_b32 m0, s63
	v_lshl_add_u64 v[246:247], s[52:53], 0, v[178:179]
	global_load_lds_dwordx4 v[244:245], off
	s_mov_b32 m0, s64
	s_nop 0
	global_load_lds_dwordx4 v[246:247], off
	s_waitcnt vmcnt(8)
	s_waitcnt lgkmcnt(0)
	s_barrier
	s_setprio 1
	s_waitcnt lgkmcnt(0)
	v_mfma_f32_16x16x32_bf16 v[88:91], v[128:131], v[160:163], v[88:91]
	v_mfma_f32_16x16x32_bf16 v[92:95], v[136:139], v[160:163], v[92:95]
	v_mfma_f32_16x16x32_bf16 v[76:79], v[128:131], v[168:171], v[76:79]
	v_mfma_f32_16x16x32_bf16 v[84:87], v[136:139], v[168:171], v[84:87]
	v_mfma_f32_16x16x32_bf16 v[120:123], v[128:131], v[186:189], v[120:123]
	v_mfma_f32_16x16x32_bf16 v[124:127], v[136:139], v[186:189], v[124:127]
	v_mfma_f32_16x16x32_bf16 v[108:111], v[128:131], v[224:227], v[108:111]
	v_mfma_f32_16x16x32_bf16 v[116:119], v[136:139], v[224:227], v[116:119]
	v_mfma_f32_16x16x32_bf16 v[88:91], v[132:135], v[164:167], v[88:91]
	v_mfma_f32_16x16x32_bf16 v[92:95], v[140:143], v[164:167], v[92:95]
	v_mfma_f32_16x16x32_bf16 v[76:79], v[132:135], v[172:175], v[76:79]
	v_mfma_f32_16x16x32_bf16 v[84:87], v[140:143], v[172:175], v[84:87]
	v_mfma_f32_16x16x32_bf16 v[120:123], v[132:135], v[196:199], v[120:123]
	v_mfma_f32_16x16x32_bf16 v[124:127], v[140:143], v[196:199], v[124:127]
	v_mfma_f32_16x16x32_bf16 v[108:111], v[132:135], v[238:241], v[108:111]
	v_mfma_f32_16x16x32_bf16 v[116:119], v[140:143], v[238:241], v[116:119]
	s_setprio 0
	s_setprio 1
	v_mfma_f32_16x16x32_bf16 v[64:67], v[144:147], v[160:163], v[64:67]
	v_mfma_f32_16x16x32_bf16 v[80:83], v[152:155], v[160:163], v[80:83]
	v_mfma_f32_16x16x32_bf16 v[48:51], v[144:147], v[168:171], v[48:51]
	v_mfma_f32_16x16x32_bf16 v[52:55], v[152:155], v[168:171], v[52:55]
	v_mfma_f32_16x16x32_bf16 v[104:107], v[144:147], v[186:189], v[104:107]
	v_mfma_f32_16x16x32_bf16 v[112:115], v[152:155], v[186:189], v[112:115]
	v_mfma_f32_16x16x32_bf16 v[96:99], v[144:147], v[224:227], v[96:99]
	v_mfma_f32_16x16x32_bf16 v[100:103], v[152:155], v[224:227], v[100:103]
	v_mfma_f32_16x16x32_bf16 v[64:67], v[148:151], v[164:167], v[64:67]
	v_mfma_f32_16x16x32_bf16 v[80:83], v[156:159], v[164:167], v[80:83]
	v_mfma_f32_16x16x32_bf16 v[48:51], v[148:151], v[172:175], v[48:51]
	v_mfma_f32_16x16x32_bf16 v[52:55], v[156:159], v[172:175], v[52:55]
	v_mfma_f32_16x16x32_bf16 v[104:107], v[148:151], v[196:199], v[104:107]
	v_mfma_f32_16x16x32_bf16 v[112:115], v[156:159], v[196:199], v[112:115]
	v_mfma_f32_16x16x32_bf16 v[96:99], v[148:151], v[238:241], v[96:99]
	v_mfma_f32_16x16x32_bf16 v[100:103], v[156:159], v[238:241], v[100:103]
	s_setprio 0
	s_barrier
	s_add_i32 s55, 0, 0x18000
	s_add_i32 s75, 0, 0x1c000
	v_add_u32_e32 v140, s55, v203
	v_add_u32_e32 v156, s75, v203
	ds_read_b128 v[128:131], v140
	ds_read_b128 v[132:135], v140 offset:1024
	ds_read_b128 v[136:139], v140 offset:2048
	ds_read_b128 v[140:143], v140 offset:3072
	ds_read_b128 v[144:147], v156
	ds_read_b128 v[148:151], v156 offset:1024
	ds_read_b128 v[152:155], v156 offset:2048
	ds_read_b128 v[156:159], v156 offset:3072
	s_add_u32 s52, s52, s80
	s_addc_u32 s53, s53, 0
	s_mov_b32 m0, s65
	v_lshl_add_u64 v[248:249], s[52:53], 0, v[180:181]
	ds_read_b128 v[160:163], v231 offset:32768
	ds_read_b128 v[164:167], v231 offset:33792
	ds_read_b128 v[168:171], v231 offset:34816
	ds_read_b128 v[172:175], v231 offset:35840
	ds_read_b128 v[186:189], v231 offset:36864
	ds_read_b128 v[196:199], v231 offset:37888
	ds_read_b128 v[224:227], v231 offset:38912
	ds_read_b128 v[238:241], v231 offset:39936
	global_load_lds_dwordx4 v[248:249], off
	v_lshl_add_u64 v[248:249], s[52:53], 0, v[178:179]
	s_mov_b32 m0, s66
	s_nop 0
	global_load_lds_dwordx4 v[248:249], off
	s_waitcnt vmcnt(8)
	s_waitcnt lgkmcnt(0)
	s_barrier
	s_setprio 1
	s_waitcnt lgkmcnt(0)
	v_mfma_f32_16x16x32_bf16 v[68:71], v[128:131], v[160:163], v[68:71]
	v_mfma_f32_16x16x32_bf16 v[72:75], v[136:139], v[160:163], v[72:75]
	v_mfma_f32_16x16x32_bf16 v[8:11], v[128:131], v[168:171], v[8:11]
	v_mfma_f32_16x16x32_bf16 v[16:19], v[136:139], v[168:171], v[16:19]
	v_mfma_f32_16x16x32_bf16 v[56:59], v[128:131], v[186:189], v[56:59]
	v_mfma_f32_16x16x32_bf16 v[60:63], v[136:139], v[186:189], v[60:63]
	v_mfma_f32_16x16x32_bf16 v[36:39], v[128:131], v[224:227], v[36:39]
	v_mfma_f32_16x16x32_bf16 v[44:47], v[136:139], v[224:227], v[44:47]
	v_mfma_f32_16x16x32_bf16 v[68:71], v[132:135], v[164:167], v[68:71]
	v_mfma_f32_16x16x32_bf16 v[72:75], v[140:143], v[164:167], v[72:75]
	v_mfma_f32_16x16x32_bf16 v[8:11], v[132:135], v[172:175], v[8:11]
	v_mfma_f32_16x16x32_bf16 v[16:19], v[140:143], v[172:175], v[16:19]
	v_mfma_f32_16x16x32_bf16 v[56:59], v[132:135], v[196:199], v[56:59]
	v_mfma_f32_16x16x32_bf16 v[60:63], v[140:143], v[196:199], v[60:63]
	v_mfma_f32_16x16x32_bf16 v[36:39], v[132:135], v[238:241], v[36:39]
	v_mfma_f32_16x16x32_bf16 v[44:47], v[140:143], v[238:241], v[44:47]
	s_setprio 0
	s_setprio 1
	v_mfma_f32_16x16x32_bf16 v[12:15], v[144:147], v[160:163], v[12:15]
	v_mfma_f32_16x16x32_bf16 v[20:23], v[152:155], v[160:163], v[20:23]
	v_mfma_f32_16x16x32_bf16 v[0:3], v[144:147], v[168:171], v[0:3]
	v_mfma_f32_16x16x32_bf16 v[4:7], v[152:155], v[168:171], v[4:7]
	v_mfma_f32_16x16x32_bf16 v[32:35], v[144:147], v[186:189], v[32:35]
	v_mfma_f32_16x16x32_bf16 v[40:43], v[152:155], v[186:189], v[40:43]
	v_mfma_f32_16x16x32_bf16 v[24:27], v[144:147], v[224:227], v[24:27]
	v_mfma_f32_16x16x32_bf16 v[28:31], v[152:155], v[224:227], v[28:31]
	v_mfma_f32_16x16x32_bf16 v[12:15], v[148:151], v[164:167], v[12:15]
	v_mfma_f32_16x16x32_bf16 v[20:23], v[156:159], v[164:167], v[20:23]
	v_mfma_f32_16x16x32_bf16 v[0:3], v[148:151], v[172:175], v[0:3]
	v_mfma_f32_16x16x32_bf16 v[4:7], v[156:159], v[172:175], v[4:7]
	v_mfma_f32_16x16x32_bf16 v[32:35], v[148:151], v[196:199], v[32:35]
	v_mfma_f32_16x16x32_bf16 v[40:43], v[156:159], v[196:199], v[40:43]
	v_mfma_f32_16x16x32_bf16 v[24:27], v[148:151], v[238:241], v[24:27]
	v_mfma_f32_16x16x32_bf16 v[28:31], v[156:159], v[238:241], v[28:31]
	s_setprio 0
	s_barrier
	s_nop 0
	s_add_i32 s52, s55, s62
	v_lshl_add_u64 v[190:191], v[190:191], 0, s[2:3]
	s_mov_b32 m0, s52
	ds_read_b128 v[160:163], v231 offset:49152
	ds_read_b128 v[164:167], v231 offset:50176
	ds_read_b128 v[168:171], v231 offset:51200
	ds_read_b128 v[172:175], v231 offset:52224
	ds_read_b128 v[186:189], v231 offset:53248
	ds_read_b128 v[196:199], v231 offset:54272
	ds_read_b128 v[224:227], v231 offset:55296
	ds_read_b128 v[238:241], v231 offset:56320
	global_load_lds_dwordx4 v[190:191], off
	v_lshl_add_u64 v[190:191], v[200:201], 0, s[2:3]
	s_add_i32 m0, s52, 0x2000
	s_add_i32 s52, s75, s62
	global_load_lds_dwordx4 v[190:191], off
	v_lshl_add_u64 v[190:191], v[234:235], 0, s[2:3]
	s_mov_b32 m0, s52
	s_nop 0
	global_load_lds_dwordx4 v[190:191], off
	v_lshl_add_u64 v[190:191], v[242:243], 0, s[2:3]
	s_add_i32 m0, s52, 0x2000
	s_nop 0
	global_load_lds_dwordx4 v[190:191], off
	v_lshl_add_u64 v[190:191], v[244:245], 0, s[2:3]
	s_mov_b32 m0, s69
	s_nop 0
	global_load_lds_dwordx4 v[190:191], off
	v_lshl_add_u64 v[190:191], v[246:247], 0, s[2:3]
	s_mov_b32 m0, s70
	s_nop 0
	global_load_lds_dwordx4 v[190:191], off
	s_waitcnt vmcnt(8)
	s_waitcnt lgkmcnt(0)
	s_barrier
	s_setprio 1
	s_waitcnt lgkmcnt(0)
	v_mfma_f32_16x16x32_bf16 v[88:91], v[128:131], v[160:163], v[88:91]
	v_mfma_f32_16x16x32_bf16 v[92:95], v[136:139], v[160:163], v[92:95]
	v_mfma_f32_16x16x32_bf16 v[76:79], v[128:131], v[168:171], v[76:79]
	v_mfma_f32_16x16x32_bf16 v[84:87], v[136:139], v[168:171], v[84:87]
	v_mfma_f32_16x16x32_bf16 v[120:123], v[128:131], v[186:189], v[120:123]
	v_mfma_f32_16x16x32_bf16 v[124:127], v[136:139], v[186:189], v[124:127]
	v_mfma_f32_16x16x32_bf16 v[108:111], v[128:131], v[224:227], v[108:111]
	v_mfma_f32_16x16x32_bf16 v[116:119], v[136:139], v[224:227], v[116:119]
	v_mfma_f32_16x16x32_bf16 v[88:91], v[132:135], v[164:167], v[88:91]
	v_mfma_f32_16x16x32_bf16 v[92:95], v[140:143], v[164:167], v[92:95]
	v_mfma_f32_16x16x32_bf16 v[76:79], v[132:135], v[172:175], v[76:79]
	v_mfma_f32_16x16x32_bf16 v[84:87], v[140:143], v[172:175], v[84:87]
	v_mfma_f32_16x16x32_bf16 v[120:123], v[132:135], v[196:199], v[120:123]
	v_mfma_f32_16x16x32_bf16 v[124:127], v[140:143], v[196:199], v[124:127]
	v_mfma_f32_16x16x32_bf16 v[108:111], v[132:135], v[238:241], v[108:111]
	v_mfma_f32_16x16x32_bf16 v[116:119], v[140:143], v[238:241], v[116:119]
	s_setprio 0
	s_setprio 1
	v_mfma_f32_16x16x32_bf16 v[64:67], v[144:147], v[160:163], v[64:67]
	v_mfma_f32_16x16x32_bf16 v[80:83], v[152:155], v[160:163], v[80:83]
	v_mfma_f32_16x16x32_bf16 v[48:51], v[144:147], v[168:171], v[48:51]
	v_mfma_f32_16x16x32_bf16 v[52:55], v[152:155], v[168:171], v[52:55]
	v_mfma_f32_16x16x32_bf16 v[104:107], v[144:147], v[186:189], v[104:107]
	v_mfma_f32_16x16x32_bf16 v[112:115], v[152:155], v[186:189], v[112:115]
	v_mfma_f32_16x16x32_bf16 v[96:99], v[144:147], v[224:227], v[96:99]
	v_mfma_f32_16x16x32_bf16 v[100:103], v[152:155], v[224:227], v[100:103]
	v_mfma_f32_16x16x32_bf16 v[64:67], v[148:151], v[164:167], v[64:67]
	v_mfma_f32_16x16x32_bf16 v[80:83], v[156:159], v[164:167], v[80:83]
	v_mfma_f32_16x16x32_bf16 v[48:51], v[148:151], v[172:175], v[48:51]
	v_mfma_f32_16x16x32_bf16 v[52:55], v[156:159], v[172:175], v[52:55]
	v_mfma_f32_16x16x32_bf16 v[104:107], v[148:151], v[196:199], v[104:107]
	v_mfma_f32_16x16x32_bf16 v[112:115], v[156:159], v[196:199], v[112:115]
	v_mfma_f32_16x16x32_bf16 v[96:99], v[148:151], v[238:241], v[96:99]
	v_mfma_f32_16x16x32_bf16 v[100:103], v[156:159], v[238:241], v[100:103]
	s_setprio 0
	s_barrier
	s_add_u32 s51, s51, 0x100
	s_addc_u32 s74, s74, 0
	s_add_u32 s12, s12, 0x100
	s_addc_u32 s13, s13, 0
	s_cmp_ge_u32 s54, s72
	s_mov_b32 s52, s54
	s_cbranch_scc0 .LBB0_668
	s_and_b64 vcc, exec, s[36:37]
	s_cbranch_vccz .LBB0_671
	s_barrier
